# DN step C2: 9 serialized LDS u16 reads batched into one wait (renamed into free VGPRs)
# speedup vs baseline: 1.0132x; 1.0029x over previous
.LBB0_705:
	v_mov_b32_e32 v0, s60
	v_cndmask_b32_e64 v155, v111, v0, s[6:7]
	s_add_i32 s18, 16, 0x21000
	s_add_i32 s19, 16, 0x8800
	v_mov_b32_e32 v3, v120
	v_mov_b32_e32 v0, v107
	v_mov_b32_e32 v74, v121
	s_and_b64 s[0:1], s[14:15], exec
	s_waitcnt lgkmcnt(0)
	s_barrier
	s_cselect_b32 s0, s19, s18
	v_mul_lo_u32 v0, v3, s24
	s_add_i32 s1, 16, 0x16400
	v_lshlrev_b32_e32 v68, 3, v74
	v_add3_u32 v0, s1, v0, v68
	v_add_u32_e32 v1, 0x1000, v0
	v_mul_lo_u32 v69, v3, 40
	v_lshl_add_u32 v3, v3, 1, s43
	v_mul_lo_u32 v74, v74, s25
	ds_read2_b64 v[64:67], v1 offset0:64 offset1:68
	v_add_u32_e32 v1, 0x1800, v0
	v_add3_u32 v68, s40, v68, v69
	v_add_u32_e32 v156, v3, v74
	ds_read_b64 v[72:73], v0 offset:2304
	ds_read2_b64 v[60:63], v1 offset0:96 offset1:100
	ds_read_b64 v[0:1], v0 offset:6976
	ds_read2_b64 v[84:87], v68 offset1:80
	ds_read2_b64 v[68:71], v68 offset0:160 offset1:240
	ds_read_u16 v188, v156 offset:61696
	v_add_u32_e32 v75, 0xd000, v3
	v_add_u32_e32 v101, 0x6510, v74
	v_add_u32_e32 v162, v75, v101
	ds_read_u16 v77, v162
	ds_read_u16 v189, v156 offset:62224
	v_add_u32_e32 v102, 0x6720, v74
	v_add_u32_e32 v163, v75, v102
	ds_read_u16 v78, v163
	v_add_u32_e32 v100, 0x6300, v74
	ds_read_u16 v190, v156 offset:62752
	v_add_u32_e32 v96, 0x4200, v74
	v_add_u32_e32 v97, 0x4410, v74
	v_add_u32_e32 v98, 0x4620, v74
	v_add_u32_e32 v99, 0x4830, v74
	v_add_u32_e32 v74, 0x6930, v74
	v_add_u32_e32 v164, v75, v74
	v_add_u32_e32 v157, v75, v96
	v_add_u32_e32 v158, v75, v97
	v_add_u32_e32 v159, v75, v98
	v_add_u32_e32 v160, v75, v99
	v_add_u32_e32 v161, v75, v100
	ds_read_u16 v192, v164
	ds_read_u16 v191, v156 offset:63280
	v_add_u32_e32 v75, 0xd020, v3
	ds_read_u16 v193, v157
	v_add_u32_e32 v181, v75, v97
	v_add_u32_e32 v185, v75, v101
	v_add_u32_e32 v182, v75, v98
	v_add_u32_e32 v186, v75, v102
	ds_read_u16 v194, v158
	v_add_u32_e32 v180, v75, v96
	v_add_u32_e32 v183, v75, v99
	v_add_u32_e32 v184, v75, v100
	v_add_u32_e32 v187, v75, v74
	ds_read_u16 v195, v159
	ds_read_u16 v196, v160
	ds_read_u16 v76, v161
	s_waitcnt lgkmcnt(1)
	v_lshlrev_b32_e32 v88, 16, v188
	v_lshlrev_b32_e32 v89, 16, v189
	v_lshlrev_b32_e32 v90, 16, v190
	v_lshlrev_b32_e32 v77, 16, v77
	v_lshlrev_b32_e32 v78, 16, v78
	v_lshlrev_b32_e32 v79, 16, v192
	v_lshlrev_b32_e32 v91, 16, v191
	v_lshlrev_b32_e32 v80, 16, v193
	v_lshlrev_b32_e32 v81, 16, v194
	v_lshlrev_b32_e32 v82, 16, v195
	v_lshlrev_b32_e32 v83, 16, v196
	ds_read_u16 v168, v156 offset:53248
	ds_read_u16 v3, v156 offset:53280
	ds_read_u16 v92, v156 offset:53808
	ds_read_u16 v93, v156 offset:62256
	ds_read_u16 v97, v181
	ds_read_u16 v101, v185
	ds_read_u16 v94, v156 offset:62784
	ds_read_u16 v98, v182
	ds_read_u16 v102, v186
	s_waitcnt lgkmcnt(6)
	v_lshlrev_b32_e32 v165, 16, v92
	ds_read_u16 v92, v156 offset:54336
	ds_read_u16 v95, v156 offset:63312
	ds_read_u16 v99, v183
	ds_read_u16 v74, v187
	ds_read_u16 v96, v180
	ds_read_u16 v100, v184
	s_waitcnt lgkmcnt(5)
	v_lshlrev_b32_e32 v166, 16, v92
	ds_read_u16 v92, v156 offset:54864
	v_lshlrev_b32_e32 v3, 16, v3
	v_lshlrev_b32_e32 v76, 16, v76
	v_lshlrev_b32_e32 v93, 16, v93
	v_lshlrev_b32_e32 v94, 16, v94
	s_waitcnt lgkmcnt(0)
	v_lshlrev_b32_e32 v167, 16, v92
	ds_read_u16 v92, v156 offset:61728
	ds_read_u16 v169, v156 offset:54832
	ds_read_u16 v170, v156 offset:53776
	ds_read_u16 v171, v156 offset:54304
	v_lshlrev_b32_e32 v95, 16, v95
	v_lshlrev_b32_e32 v96, 16, v96
	v_lshlrev_b32_e32 v97, 16, v97
	s_waitcnt lgkmcnt(3)
	v_lshlrev_b32_e32 v92, 16, v92
	v_lshlrev_b32_e32 v98, 16, v98
	v_lshlrev_b32_e32 v99, 16, v99
	v_lshlrev_b32_e32 v100, 16, v100
	v_lshlrev_b32_e32 v101, 16, v101
	v_lshlrev_b32_e32 v102, 16, v102
	v_lshlrev_b32_e32 v103, 16, v74
	v_mov_b32_e32 v140, v84
	v_mov_b32_e32 v141, v85
	v_mov_b32_e32 v142, v2
	v_mov_b32_e32 v143, v2
	s_waitcnt lgkmcnt(2)
	v_lshlrev_b32_e32 v84, 16, v169
	v_lshlrev_b32_e32 v85, 16, v168
	s_waitcnt lgkmcnt(1)
	v_lshlrev_b32_e32 v168, 16, v170
	s_waitcnt lgkmcnt(0)
	v_lshlrev_b32_e32 v169, 16, v171
	v_cvt_pk_bf16_f32 v169, v169, v84
	v_cvt_pk_bf16_f32 v168, v85, v168
	v_mov_b32_e32 v170, v2
	v_mov_b32_e32 v171, v2
	v_mov_b32_e32 v74, v2
	v_mov_b32_e32 v75, v2
	v_mfma_f32_16x16x32_bf16 v[168:171], v[140:143], v[168:171], 0
	v_cvt_pk_bf16_f32 v173, v166, v167
	v_cvt_pk_bf16_f32 v172, v3, v165
	v_mov_b32_e32 v174, v2
	v_mov_b32_e32 v175, v2
	v_mov_b32_e32 v84, v86
	v_mov_b32_e32 v85, v87
	v_mfma_f32_16x16x32_bf16 v[140:143], v[140:143], v[172:175], 0
	s_nop 0
	v_cvt_pk_bf16_f32 v173, v170, v171
	v_cvt_pk_bf16_f32 v172, v168, v169
	v_mov_b32_e32 v86, v2
	v_mov_b32_e32 v87, v2
	v_mfma_f32_16x16x32_bf16 v[88:91], v[72:75], v[172:175], v[88:91]
	v_mov_b32_e32 v176, v2
	v_mov_b32_e32 v177, v2
	v_mov_b32_e32 v178, v2
	v_mov_b32_e32 v179, v2
	v_mov_b32_e32 v3, v2
	s_nop 2
	v_cvt_pk_bf16_f32 v175, v90, v91
	v_cvt_pk_bf16_f32 v174, v88, v89
	s_cmp_lg_u32 16, -1
	s_cselect_b32 s1, s41, 0
	v_mfma_f32_16x16x32_bf16 v[88:91], v[84:87], v[174:177], 0
	v_cvt_pk_bf16_f32 v177, v142, v143
	v_cvt_pk_bf16_f32 v176, v140, v141
	s_nop 1
	v_mfma_f32_16x16x32_bf16 v[72:75], v[72:75], v[176:179], v[92:95]
	s_nop 2
	v_cvt_pk_bf16_f32 v175, v90, v91
	v_cvt_pk_bf16_f32 v174, v88, v89
	v_mov_b32_e32 v94, v2
	v_mov_b32_e32 v95, v2
	s_nop 0
	v_cvt_pk_bf16_f32 v93, v74, v75
	v_cvt_pk_bf16_f32 v92, v72, v73
	v_mfma_f32_16x16x32_bf16 v[80:83], v[64:67], v[172:175], v[80:83]
	s_nop 0
	v_mfma_f32_16x16x32_bf16 v[72:75], v[84:87], v[92:95], 0
	v_mov_b32_e32 v84, v68
	v_mov_b32_e32 v85, v69
	s_nop 3
	v_cvt_pk_bf16_f32 v93, v82, v83
	v_cvt_pk_bf16_f32 v92, v80, v81
	v_mfma_f32_16x16x32_bf16 v[76:79], v[60:63], v[172:175], v[76:79]
	v_cvt_pk_bf16_f32 v179, v74, v75
	v_cvt_pk_bf16_f32 v178, v72, v73
	v_mov_b32_e32 v68, v2
	v_mfma_f32_16x16x32_bf16 v[80:83], v[84:87], v[92:95], 0
	v_mov_b32_e32 v69, v2
	v_mfma_f32_16x16x32_bf16 v[64:67], v[64:67], v[176:179], v[96:99]
	v_mfma_f32_16x16x32_bf16 v[60:63], v[60:63], v[176:179], v[100:103]
	s_nop 6
	v_cvt_pk_bf16_f32 v67, v66, v67
	v_cvt_pk_bf16_f32 v66, v64, v65
	s_nop 1
	v_mfma_f32_16x16x32_bf16 v[64:67], v[84:87], v[66:69], 0
	v_cvt_pk_bf16_f32 v85, v82, v83
	v_cvt_pk_bf16_f32 v84, v80, v81
	v_mov_b32_e32 v68, v70
	v_mov_b32_e32 v69, v71
	v_mov_b32_e32 v70, v2
	v_mov_b32_e32 v71, v2
	v_mfma_f32_16x16x32_bf16 v[76:79], v[0:3], v[84:87], v[76:79]
	s_nop 7
	v_cvt_pk_bf16_f32 v85, v78, v79
	v_cvt_pk_bf16_f32 v84, v76, v77
	s_nop 1
	v_mfma_f32_16x16x32_bf16 v[76:79], v[68:71], v[84:87], 0
	v_cvt_pk_bf16_f32 v85, v66, v67
	v_cvt_pk_bf16_f32 v84, v64, v65
	s_nop 1
	v_mfma_f32_16x16x32_bf16 v[60:63], v[0:3], v[84:87], v[60:63]
	v_cvt_pk_bf16_f32 v87, v30, v31
	v_cvt_pk_bf16_f32 v86, v28, v29
	v_cvt_pk_bf16_f32 v85, v34, v35
	v_cvt_pk_bf16_f32 v84, v32, v33
	s_nop 3
	v_cvt_pk_bf16_f32 v1, v62, v63
	v_cvt_pk_bf16_f32 v0, v60, v61
	s_nop 1
	v_mfma_f32_16x16x32_bf16 v[60:63], v[68:71], v[0:3], 0
	v_cvt_pk_bf16_f32 v0, v168, s0
	ds_write_b16 v156, v0 offset:53248
	v_cvt_pk_bf16_f32 v0, v169, s0
	ds_write_b16 v156, v0 offset:53776
	v_cvt_pk_bf16_f32 v0, v170, s0
	ds_write_b16 v156, v0 offset:54304
	v_cvt_pk_bf16_f32 v0, v171, s0
	ds_write_b16 v156, v0 offset:54832
	v_cvt_pk_bf16_f32 v0, v88, s0
	ds_write_b16 v156, v0 offset:61696
	v_cvt_pk_bf16_f32 v0, v89, s0
	ds_write_b16 v156, v0 offset:62224
	v_cvt_pk_bf16_f32 v0, v90, s0
	ds_write_b16 v156, v0 offset:62752
	v_cvt_pk_bf16_f32 v0, v91, s0
	ds_write_b16 v156, v0 offset:63280
	v_cvt_pk_bf16_f32 v0, v80, s0
	ds_write_b16 v157, v0
	v_cvt_pk_bf16_f32 v0, v81, s0
	ds_write_b16 v158, v0
	v_cvt_pk_bf16_f32 v0, v82, s0
	ds_write_b16 v159, v0
	v_cvt_pk_bf16_f32 v0, v83, s0
	ds_write_b16 v160, v0
	v_cvt_pk_bf16_f32 v0, v76, s0
	ds_write_b16 v161, v0
	v_cvt_pk_bf16_f32 v0, v77, s0
	ds_write_b16 v162, v0
	v_cvt_pk_bf16_f32 v0, v78, s0
	ds_write_b16 v163, v0
	v_cvt_pk_bf16_f32 v0, v79, s0
	ds_write_b16 v164, v0
	v_cvt_pk_bf16_f32 v0, v140, s0
	ds_write_b16 v156, v0 offset:53280
	v_cvt_pk_bf16_f32 v0, v141, s0
	ds_write_b16 v156, v0 offset:53808
	v_cvt_pk_bf16_f32 v0, v142, s0
	ds_write_b16 v156, v0 offset:54336
	v_cvt_pk_bf16_f32 v0, v143, s0
	ds_write_b16 v156, v0 offset:54864
	v_cvt_pk_bf16_f32 v0, v72, s0
	ds_write_b16 v156, v0 offset:61728
	v_cvt_pk_bf16_f32 v0, v73, s0
	ds_write_b16 v156, v0 offset:62256
	v_cvt_pk_bf16_f32 v0, v74, s0
	ds_write_b16 v156, v0 offset:62784
	v_cvt_pk_bf16_f32 v0, v75, s0
	ds_write_b16 v156, v0 offset:63312
	v_cvt_pk_bf16_f32 v0, v64, s0
	ds_write_b16 v180, v0
	v_cvt_pk_bf16_f32 v0, v65, s0
	ds_write_b16 v181, v0
	v_cvt_pk_bf16_f32 v0, v66, s0
	ds_write_b16 v182, v0
	v_cvt_pk_bf16_f32 v0, v67, s0
	ds_write_b16 v183, v0
	v_cvt_pk_bf16_f32 v0, v60, s0
	ds_write_b16 v184, v0
	v_cvt_pk_bf16_f32 v0, v61, s0
	ds_write_b16 v185, v0
	v_cvt_pk_bf16_f32 v0, v62, s0
	ds_write_b16 v186, v0
	v_cvt_pk_bf16_f32 v0, v63, s0
	v_mov_b32_e32 v3, v107
	v_mov_b32_e32 v88, v120
	v_mov_b32_e32 v89, v121
	ds_write_b16 v187, v0
	s_waitcnt lgkmcnt(0)
	s_barrier
	v_cvt_pk_bf16_f32 v63, v6, v7
	v_mul_lo_u32 v0, v88, s22
	v_lshlrev_b32_e32 v90, 3, v89
	v_add3_u32 v164, 16, v0, v90
	v_add_u32_e32 v0, 0xd000, v164
	ds_read2_b64 v[72:75], v0 offset0:32 offset1:36
	ds_read2_b64 v[76:79], v0 offset0:40 offset1:44
	v_cvt_pk_bf16_f32 v62, v4, v5
	v_cvt_pk_bf16_f32 v61, v10, v11
	v_cvt_pk_bf16_f32 v60, v8, v9
	ds_read2_b64 v[80:83], v0 offset0:48 offset1:52
	v_cvt_pk_bf16_f32 v67, v14, v15
	s_waitcnt lgkmcnt(2)
	v_mfma_f32_16x16x32_bf16 v[72:75], v[72:75], v[60:63], 0
	v_cvt_pk_bf16_f32 v66, v12, v13
	v_cvt_pk_bf16_f32 v65, v18, v19
	v_cvt_pk_bf16_f32 v64, v16, v17
	ds_read2_b64 v[92:95], v0 offset0:56 offset1:60
	v_mul_lo_u32 v0, v88, s21
	s_waitcnt lgkmcnt(2)
	v_mfma_f32_16x16x32_bf16 v[72:75], v[76:79], v[64:67], v[72:75]
	v_cvt_pk_bf16_f32 v71, v22, v23
	v_cvt_pk_bf16_f32 v70, v20, v21
	v_cvt_pk_bf16_f32 v69, v26, v27
	v_cvt_pk_bf16_f32 v68, v24, v25
	v_add3_u32 v165, s66, v90, v0
	ds_read2_b64 v[76:79], v165 offset1:4
	s_waitcnt lgkmcnt(2)
	v_mfma_f32_16x16x32_bf16 v[72:75], v[80:83], v[68:71], v[72:75]
	v_add_u32_e32 v1, 0xf000, v164
	ds_read2_b64 v[98:101], v1 offset0:80 offset1:84
	v_add_u32_e32 v91, 0x1000, v165
	s_waitcnt lgkmcnt(2)
	v_mfma_f32_16x16x32_bf16 v[80:83], v[92:95], v[84:87], v[72:75]
	ds_read2_b64 v[92:95], v165 offset0:16 offset1:20
	v_lshl_add_u32 v0, v88, 1, s61
	v_mad_u64_u32 v[102:103], s[12:13], v89, s25, v[0:1]
	ds_read2_b64 v[72:75], v165 offset0:8 offset1:12
	s_waitcnt lgkmcnt(3)
	v_mfma_f32_16x16x32_bf16 v[76:79], v[76:79], v[60:63], 0
	s_waitcnt lgkmcnt(0)
	v_mfma_f32_16x16x32_bf16 v[72:75], v[72:75], v[64:67], v[76:79]
	s_nop 5
	ds_read2_b64 v[76:79], v165 offset0:24 offset1:28
	v_mfma_f32_16x16x32_bf16 v[72:75], v[92:95], v[68:71], v[72:75]
	ds_read2_b64 v[94:97], v1 offset0:64 offset1:68
	v_lshlrev_b32_e32 v92, 2, v89
	v_or_b32_e32 v176, 1, v92
	s_waitcnt lgkmcnt(1)
	v_mfma_f32_16x16x32_bf16 v[72:75], v[76:79], v[84:87], v[72:75]
	ds_read2_b64 v[76:79], v1 offset0:72 offset1:76
	v_mad_u64_u32 v[160:161], s[12:13], v176, s22, v[0:1]
	s_waitcnt lgkmcnt(1)
	v_mfma_f32_16x16x32_bf16 v[94:97], v[94:97], v[60:63], 0
	v_add_u32_e32 v172, 0x1ef0, v160
	s_cselect_b32 s12, 16, 0
	s_add_u32 s12, s12, 0x1c8fc
	s_waitcnt lgkmcnt(0)
	v_mfma_f32_16x16x32_bf16 v[76:79], v[76:79], v[64:67], v[94:97]
	s_addc_u32 s13, s1, 0
	s_nop 1
	ds_read2_b64 v[94:97], v91 offset0:32 offset1:36
	s_cmp_lg_u64 s[12:13], 0
	v_mfma_f32_16x16x32_bf16 v[76:79], v[98:101], v[68:71], v[76:79]
	ds_read2_b64 v[98:101], v1 offset0:88 offset1:92
	ds_read_u16 v0, v102 offset:53248
	ds_read_u16 v1, v160 offset:53248
	ds_read_u16 v93, v160 offset:53776
	ds_read_u16 v102, v160 offset:54304
	ds_read_u16 v161, v160 offset:61168
	ds_read_u16 v162, v160 offset:61696
	ds_read_u16 v166, v160 offset:62224
	ds_read_u16 v167, v160 offset:62752
	ds_read2_b64 v[140:143], v91 offset0:40 offset1:44
	s_waitcnt lgkmcnt(7)
	v_lshlrev_b32_e32 v1, 16, v1
	v_mfma_f32_16x16x32_bf16 v[94:97], v[94:97], v[60:63], 0
	v_lshlrev_b32_e32 v0, 16, v0
	v_pk_add_f32 v[0:1], v[0:1], v[80:81] neg_lo:[0,1] neg_hi:[0,1]
	v_add_u32_e32 v80, 0x4200, v164
	v_mfma_f32_16x16x32_bf16 v[98:101], v[98:101], v[84:87], v[76:79]
	v_add_u32_e32 v168, 0xd000, v80
	s_waitcnt lgkmcnt(5)
	v_lshlrev_b32_e32 v81, 16, v102
	ds_read2_b64 v[156:159], v91 offset0:56 offset1:60
	ds_read2_b64 v[76:79], v91 offset0:48 offset1:52
	s_waitcnt lgkmcnt(2)
	v_mfma_f32_16x16x32_bf16 v[94:97], v[140:143], v[64:67], v[94:97]
	ds_read2_b64 v[140:143], v168 offset0:32 offset1:36
	v_lshlrev_b32_e32 v80, 16, v93
	v_pk_add_f32 v[102:103], v[80:81], v[82:83] neg_lo:[0,1] neg_hi:[0,1]
	ds_read2_b64 v[80:83], v168 offset0:40 offset1:44
	s_waitcnt lgkmcnt(2)
	v_mfma_f32_16x16x32_bf16 v[76:79], v[76:79], v[68:71], v[94:97]
	s_nop 2
	ds_read2_b64 v[94:97], v168 offset0:48 offset1:52
	v_add_u32_e32 v93, 0x2000, v165
	v_lshlrev_b32_e32 v163, 16, v162
	s_waitcnt lgkmcnt(2)
	v_mfma_f32_16x16x32_bf16 v[140:143], v[140:143], v[60:63], 0
	v_lshlrev_b32_e32 v162, 16, v161
	v_add_u32_e32 v165, 0x3000, v165
	s_cselect_b32 s1, s12, -1
	v_mfma_f32_16x16x32_bf16 v[76:79], v[156:159], v[84:87], v[76:79]
	ds_read2_b64 v[156:159], v168 offset0:56 offset1:60
	v_pk_add_f32 v[168:169], v[162:163], v[98:99] neg_lo:[0,1] neg_hi:[0,1]
	v_lshlrev_b32_e32 v99, 16, v167
	s_waitcnt lgkmcnt(2)
	v_mfma_f32_16x16x32_bf16 v[80:83], v[80:83], v[64:67], v[140:143]
	v_lshlrev_b32_e32 v98, 16, v166
	v_pk_add_f32 v[170:171], v[98:99], v[100:101] neg_lo:[0,1] neg_hi:[0,1]
	ds_read2_b64 v[98:101], v93 offset0:88 offset1:92
	ds_read2_b64 v[140:143], v93 offset0:64 offset1:68
	s_waitcnt lgkmcnt(3)
	v_mfma_f32_16x16x32_bf16 v[80:83], v[94:97], v[68:71], v[80:83]
	ds_read2_b64 v[94:97], v93 offset0:72 offset1:76
	s_add_i32 s66, 16, 0x258fc
	s_and_b64 s[12:13], s[14:15], exec
	s_waitcnt lgkmcnt(3)
	v_mfma_f32_16x16x32_bf16 v[156:159], v[156:159], v[84:87], v[80:83]
	s_cselect_b32 s1, s1, s66
	v_or_b32_e32 v177, 2, v92
	v_or_b32_e32 v178, 3, v92
	ds_read2_b64 v[80:83], v93 offset0:80 offset1:84
	s_waitcnt lgkmcnt(2)
	v_mfma_f32_16x16x32_bf16 v[140:143], v[140:143], v[60:63], 0
	v_add_u32_e32 v91, 16, v92
	v_add_u32_e32 v179, 17, v92
	v_add_u32_e32 v180, 18, v92
	s_waitcnt lgkmcnt(1)
	v_mfma_f32_16x16x32_bf16 v[94:97], v[94:97], v[64:67], v[140:143]
	v_add_u32_e32 v181, 19, v92
	v_add_u32_e32 v93, 32, v92
	v_add_u32_e32 v182, 33, v92
	s_waitcnt lgkmcnt(0)
	v_mfma_f32_16x16x32_bf16 v[80:83], v[80:83], v[68:71], v[94:97]
	v_add_u32_e32 v140, 0x3ff0, v160
	v_add_u32_e32 v187, 34, v92
	v_add_u32_e32 v188, 35, v92
	v_add_u32_e32 v94, 0x6300, v164
	v_add_u32_e32 v162, 0xd000, v94
	ds_read2_b64 v[94:97], v162 offset0:32 offset1:36
	ds_read_u16 v160, v172 offset:61696
	ds_read_u16 v141, v172 offset:62224
	ds_read_u16 v164, v172 offset:62752
	ds_read_u16 v166, v172 offset:63280
	ds_read_u16 v183, v140 offset:61696
	ds_read_u16 v184, v140 offset:62224
	ds_read_u16 v185, v140 offset:62752
	ds_read_u16 v186, v140 offset:63280
	s_waitcnt lgkmcnt(6)
	v_lshlrev_b32_e32 v161, 16, v141
	ds_read2_b64 v[140:143], v162 offset0:40 offset1:44
	v_mfma_f32_16x16x32_bf16 v[80:83], v[98:101], v[84:87], v[80:83]
	ds_read2_b64 v[98:101], v162 offset0:48 offset1:52
	v_lshlrev_b32_e32 v160, 16, v160
	v_pk_add_f32 v[172:173], v[160:161], v[156:157] neg_lo:[0,1] neg_hi:[0,1]
	v_mfma_f32_16x16x32_bf16 v[94:97], v[94:97], v[60:63], 0
	ds_read2_b64 v[160:163], v162 offset0:56 offset1:60
	s_waitcnt lgkmcnt(7)
	v_lshlrev_b32_e32 v157, 16, v166
	v_lshlrev_b32_e32 v156, 16, v164
	s_waitcnt lgkmcnt(2)
	v_mfma_f32_16x16x32_bf16 v[94:97], v[140:143], v[64:67], v[94:97]
	ds_read2_b64 v[140:143], v165 offset0:96 offset1:100
	v_pk_add_f32 v[174:175], v[156:157], v[158:159] neg_lo:[0,1] neg_hi:[0,1]
	v_add_u32_e32 v189, 49, v92
	s_waitcnt lgkmcnt(2)
	v_mfma_f32_16x16x32_bf16 v[94:97], v[98:101], v[68:71], v[94:97]
	ds_read2_b64 v[98:101], v165 offset0:104 offset1:108
	s_add_i32 s60, s60, 1
	v_cmp_lt_u32_e32 vcc, s60, v109
	s_waitcnt lgkmcnt(1)
	v_mfma_f32_16x16x32_bf16 v[60:63], v[140:143], v[60:63], 0
	v_mfma_f32_16x16x32_bf16 v[156:159], v[160:163], v[84:87], v[94:97]
	ds_read2_b64 v[160:163], v165 offset0:112 offset1:116
	ds_read2_b64 v[164:167], v165 offset0:120 offset1:124
	s_nop 0
	v_lshlrev_b32_e32 v97, 16, v184
	s_waitcnt lgkmcnt(2)
	v_mfma_f32_16x16x32_bf16 v[60:63], v[98:101], v[64:67], v[60:63]
	v_lshlrev_b32_e32 v65, 16, v186
	v_lshlrev_b32_e32 v64, 16, v185
	v_lshlrev_b32_e32 v96, 16, v183
	s_waitcnt lgkmcnt(1)
	v_mfma_f32_16x16x32_bf16 v[60:63], v[160:163], v[68:71], v[60:63]
	v_add_f32_e64 v64, v64, -v158
	v_add_f32_e64 v65, v65, -v159
	v_mul_lo_u32 v159, v88, s24
	v_pk_add_f32 v[96:97], v[96:97], v[156:157] neg_lo:[0,1] neg_hi:[0,1]
	s_waitcnt lgkmcnt(0)
	v_mfma_f32_16x16x32_bf16 v[68:71], v[164:167], v[84:87], v[60:63]
	v_cvt_pk_bf16_f32 v66, v96, v97
	v_cvt_pk_bf16_f32 v67, v64, v65
	v_cvt_pk_bf16_f32 v65, v174, v175
	v_cvt_pk_bf16_f32 v60, v0, v1
	v_mov_b32_e32 v0, s1
	s_add_i32 s1, 16, 0x19200
	v_add_u32_e32 v158, s1, v90
	v_add_u32_e32 v84, v158, v159
	ds_read2_b64 v[96:99], v84 offset1:4
	ds_read_b32 v0, v0
	v_cvt_pk_bf16_f32 v61, v102, v103
	ds_read2_b64 v[100:103], v84 offset0:8 offset1:12
	v_cvt_pk_bf16_f32 v63, v170, v171
	v_cvt_pk_bf16_f32 v62, v168, v169
	s_waitcnt lgkmcnt(1)
	v_mul_f32_e32 v157, 0x3fb8aa3b, v0
	v_lshlrev_b32_e32 v0, 6, v155
	v_lshl_add_u32 v155, v89, 4, s65
	ds_read_b128 v[140:143], v155
	v_ashrrev_i32_e32 v89, 31, v88
	v_lshl_add_u64 v[84:85], v[88:89], 2, v[116:117]
	v_mfma_f32_16x16x32_bf16 v[86:89], v[96:99], v[60:63], 0
	v_cvt_pk_bf16_f32 v64, v172, v173
	ds_read_b128 v[96:99], v155 offset:64
	s_waitcnt lgkmcnt(1)
	v_mul_f32_e32 v140, 0x3fb8aa3b, v140
	v_exp_f32_e32 v140, v140
	v_mfma_f32_16x16x32_bf16 v[86:89], v[100:103], v[64:67], v[86:89]
	v_sub_u32_e32 v100, 63, v92
	v_ashrrev_i32_e32 v1, 31, v0
	v_cndmask_b32_e64 v100, v100, v92, s[6:7]
	v_lshl_add_u64 v[0:1], v[0:1], 0, v[104:105]
	v_ashrrev_i32_e32 v101, 31, v100
	s_nop 2
	v_fma_f32 v72, v72, v140, v86
	v_lshl_add_u64 v[100:101], v[0:1], 0, v[100:101]
	v_mul_f32_e32 v86, 0x3fb8aa3b, v141
	v_lshlrev_b64 v[100:101], 12, v[100:101]
	v_exp_f32_e32 v86, v86
	v_lshl_add_u64 v[100:101], v[84:85], 0, v[100:101]
	global_store_dword v[100:101], v72, off
	v_sub_u32_e32 v72, 63, v176
	v_cndmask_b32_e64 v72, v72, v176, s[6:7]
	v_fma_f32 v86, v73, v86, v87
	v_ashrrev_i32_e32 v73, 31, v72
	v_lshl_add_u64 v[72:73], v[0:1], 0, v[72:73]
	v_lshlrev_b64 v[72:73], 12, v[72:73]
	v_lshl_add_u64 v[72:73], v[84:85], 0, v[72:73]
	v_mul_f32_e32 v87, 0x3fb8aa3b, v142
	global_store_dword v[72:73], v86, off
	v_sub_u32_e32 v72, 63, v177
	v_exp_f32_e32 v87, v87
	v_cndmask_b32_e64 v72, v72, v177, s[6:7]
	v_ashrrev_i32_e32 v73, 31, v72
	v_lshl_add_u64 v[72:73], v[0:1], 0, v[72:73]
	v_lshlrev_b64 v[72:73], 12, v[72:73]
	v_fma_f32 v74, v74, v87, v88
	v_lshl_add_u64 v[72:73], v[84:85], 0, v[72:73]
	v_add_u32_e32 v140, 0x900, v159
	global_store_dword v[72:73], v74, off
	v_mul_f32_e32 v72, 0x3fb8aa3b, v143
	v_add_u32_e32 v73, v158, v140
	v_exp_f32_e32 v72, v72
	ds_read2_b64 v[100:103], v73 offset1:4
	v_sub_u32_e32 v74, 63, v178
	v_cndmask_b32_e64 v86, v74, v178, s[6:7]
	v_fmac_f32_e32 v89, v75, v72
	ds_read2_b64 v[72:75], v73 offset0:8 offset1:12
	v_ashrrev_i32_e32 v87, 31, v86
	v_lshl_add_u64 v[86:87], v[0:1], 0, v[86:87]
	s_waitcnt lgkmcnt(1)
	v_mfma_f32_16x16x32_bf16 v[100:103], v[100:103], v[60:63], 0
	v_lshlrev_b64 v[86:87], 12, v[86:87]
	v_lshl_add_u64 v[86:87], v[84:85], 0, v[86:87]
	global_store_dword v[86:87], v89, off
	v_mul_f32_e32 v86, 0x3fb8aa3b, v96
	v_exp_f32_e32 v87, v86
	s_waitcnt lgkmcnt(0)
	v_mfma_f32_16x16x32_bf16 v[72:75], v[72:75], v[64:67], v[100:103]
	v_sub_u32_e32 v86, 47, v92
	v_cndmask_b32_e64 v86, v86, v91, s[6:7]
	v_add_u32_e32 v141, 0x1200, v159
	ds_read_b128 v[100:103], v155 offset:128
	v_add_u32_e32 v94, 48, v92
	s_nop 2
	v_fma_f32 v72, v76, v87, v72
	v_ashrrev_i32_e32 v87, 31, v86
	v_lshl_add_u64 v[86:87], v[0:1], 0, v[86:87]
	v_mul_f32_e32 v76, 0x3fb8aa3b, v97
	v_lshlrev_b64 v[86:87], 12, v[86:87]
	v_exp_f32_e32 v76, v76
	v_lshl_add_u64 v[86:87], v[84:85], 0, v[86:87]
	global_store_dword v[86:87], v72, off
	v_sub_u32_e32 v72, 46, v92
	v_cndmask_b32_e64 v72, v72, v179, s[6:7]
	v_fma_f32 v76, v77, v76, v73
	v_ashrrev_i32_e32 v73, 31, v72
	v_lshl_add_u64 v[72:73], v[0:1], 0, v[72:73]
	v_lshlrev_b64 v[72:73], 12, v[72:73]
	v_lshl_add_u64 v[72:73], v[84:85], 0, v[72:73]
	v_mul_f32_e32 v77, 0x3fb8aa3b, v98
	global_store_dword v[72:73], v76, off
	v_sub_u32_e32 v72, 45, v92
	v_exp_f32_e32 v77, v77
	v_cndmask_b32_e64 v72, v72, v180, s[6:7]
	v_ashrrev_i32_e32 v73, 31, v72
	v_lshl_add_u64 v[72:73], v[0:1], 0, v[72:73]
	v_lshlrev_b64 v[72:73], 12, v[72:73]
	v_fma_f32 v74, v78, v77, v74
	v_lshl_add_u64 v[72:73], v[84:85], 0, v[72:73]
	global_store_dword v[72:73], v74, off
	v_add_u32_e32 v74, v158, v141
	v_mul_f32_e32 v73, 0x3fb8aa3b, v99
	ds_read2_b64 v[86:89], v74 offset1:4
	v_exp_f32_e32 v73, v73
	v_sub_u32_e32 v72, 44, v92
	v_cndmask_b32_e64 v72, v72, v181, s[6:7]
	ds_read2_b64 v[96:99], v74 offset0:8 offset1:12
	v_fmac_f32_e32 v75, v79, v73
	v_ashrrev_i32_e32 v73, 31, v72
	v_lshl_add_u64 v[72:73], v[0:1], 0, v[72:73]
	v_lshlrev_b64 v[72:73], 12, v[72:73]
	v_lshl_add_u64 v[72:73], v[84:85], 0, v[72:73]
	global_store_dword v[72:73], v75, off
	s_waitcnt lgkmcnt(1)
	v_mfma_f32_16x16x32_bf16 v[72:75], v[86:89], v[60:63], 0
	ds_read_b128 v[76:79], v155 offset:192
	v_mul_f32_e32 v86, 0x3fb8aa3b, v100
	v_exp_f32_e32 v87, v86
	s_waitcnt lgkmcnt(1)
	v_mfma_f32_16x16x32_bf16 v[72:75], v[96:99], v[64:67], v[72:75]
	v_sub_u32_e32 v86, 31, v92
	v_cndmask_b32_e64 v86, v86, v93, s[6:7]
	v_add_u32_e32 v100, 0x1b00, v159
	v_add_u32_e32 v156, 50, v92
	v_add_u32_e32 v95, 51, v92
	s_nop 2
	v_fma_f32 v72, v80, v87, v72
	v_ashrrev_i32_e32 v87, 31, v86
	v_lshl_add_u64 v[86:87], v[0:1], 0, v[86:87]
	v_mul_f32_e32 v80, 0x3fb8aa3b, v101
	v_lshlrev_b64 v[86:87], 12, v[86:87]
	v_exp_f32_e32 v80, v80
	v_lshl_add_u64 v[86:87], v[84:85], 0, v[86:87]
	global_store_dword v[86:87], v72, off
	v_sub_u32_e32 v72, 30, v92
	v_cndmask_b32_e64 v72, v72, v182, s[6:7]
	v_fma_f32 v80, v81, v80, v73
	v_ashrrev_i32_e32 v73, 31, v72
	v_lshl_add_u64 v[72:73], v[0:1], 0, v[72:73]
	v_lshlrev_b64 v[72:73], 12, v[72:73]
	v_lshl_add_u64 v[72:73], v[84:85], 0, v[72:73]
	v_mul_f32_e32 v81, 0x3fb8aa3b, v102
	global_store_dword v[72:73], v80, off
	v_sub_u32_e32 v72, 29, v92
	v_exp_f32_e32 v81, v81
	v_cndmask_b32_e64 v72, v72, v187, s[6:7]
	v_ashrrev_i32_e32 v73, 31, v72
	v_lshl_add_u64 v[72:73], v[0:1], 0, v[72:73]
	v_lshlrev_b64 v[72:73], 12, v[72:73]
	v_fma_f32 v74, v82, v81, v74
	v_lshl_add_u64 v[72:73], v[84:85], 0, v[72:73]
	global_store_dword v[72:73], v74, off
	v_mul_f32_e32 v72, 0x3fb8aa3b, v103
	v_add_u32_e32 v74, v158, v100
	v_exp_f32_e32 v73, v72
	ds_read2_b64 v[86:89], v74 offset1:4
	v_sub_u32_e32 v72, 28, v92
	v_cndmask_b32_e64 v72, v72, v188, s[6:7]
	v_fmac_f32_e32 v75, v83, v73
	ds_read2_b64 v[80:83], v74 offset0:8 offset1:12
	v_ashrrev_i32_e32 v73, 31, v72
	v_lshl_add_u64 v[72:73], v[0:1], 0, v[72:73]
	s_waitcnt lgkmcnt(1)
	v_mfma_f32_16x16x32_bf16 v[86:89], v[86:89], v[60:63], 0
	v_lshlrev_b64 v[72:73], 12, v[72:73]
	v_lshl_add_u64 v[72:73], v[84:85], 0, v[72:73]
	global_store_dword v[72:73], v75, off
	v_mul_f32_e32 v72, 0x3fb8aa3b, v76
	v_exp_f32_e32 v76, v72
	s_waitcnt lgkmcnt(0)
	v_mfma_f32_16x16x32_bf16 v[72:75], v[80:83], v[64:67], v[86:89]
	v_sub_u32_e32 v80, 15, v92
	v_cndmask_b32_e64 v80, v80, v94, s[6:7]
	v_ashrrev_i32_e32 v81, 31, v80
	v_lshl_add_u64 v[80:81], v[0:1], 0, v[80:81]
	v_lshlrev_b64 v[80:81], 12, v[80:81]
	s_nop 2
	v_fma_f32 v68, v68, v76, v72
	v_mul_f32_e32 v72, 0x3fb8aa3b, v77
	v_exp_f32_e32 v72, v72
	v_lshl_add_u64 v[80:81], v[84:85], 0, v[80:81]
	global_store_dword v[80:81], v68, off
	v_sub_u32_e32 v68, 14, v92
	v_cndmask_b32_e64 v68, v68, v189, s[6:7]
	v_fma_f32 v72, v69, v72, v73
	v_ashrrev_i32_e32 v69, 31, v68
	v_add_u32_e32 v101, s0, v159
	v_lshl_add_u64 v[68:69], v[0:1], 0, v[68:69]
	v_add_u32_e32 v73, v101, v90
	v_lshlrev_b64 v[68:69], 12, v[68:69]
	ds_read2_b64 v[80:83], v73 offset1:4
	v_lshl_add_u64 v[68:69], v[84:85], 0, v[68:69]
	global_store_dword v[68:69], v72, off
	v_sub_u32_e32 v69, 13, v92
	v_cndmask_b32_e64 v72, v69, v156, s[6:7]
	v_mul_f32_e32 v69, 0x3fb8aa3b, v78
	v_exp_f32_e32 v68, v157
	v_exp_f32_e32 v69, v69
	v_xor_b32_e32 v77, 8, v91
	v_pk_mul_f32 v[8:9], v[8:9], v[68:69] op_sel_hi:[1,0]
	v_pk_mul_f32 v[10:11], v[10:11], v[68:69] op_sel_hi:[1,0]
	v_fma_f32 v69, v70, v69, v74
	v_add_u32_e32 v70, s0, v141
	s_waitcnt lgkmcnt(0)
	v_mfma_f32_16x16x32_bf16 v[8:11], v[80:83], v[60:63], v[8:11]
	ds_read2_b64 v[80:83], v73 offset0:8 offset1:12
	v_add_u32_e32 v73, s0, v140
	v_xad_u32 v76, v90, 16, v73
	v_lshl_add_u32 v77, v77, 1, v73
	ds_read_b64 v[86:87], v76
	ds_read_b64 v[88:89], v77
	v_xor_b32_e32 v76, 8, v93
	v_lshl_add_u32 v76, v76, 1, v73
	v_xor_b32_e32 v77, 8, v94
	v_lshl_add_u32 v73, v77, 1, v73
	ds_read_b64 v[96:97], v76
	ds_read_b64 v[98:99], v73
	v_xad_u32 v74, v90, 32, v70
	v_xor_b32_e32 v76, 16, v91
	s_waitcnt lgkmcnt(4)
	v_mfma_f32_16x16x32_bf16 v[8:11], v[80:83], v[64:67], v[8:11]
	v_lshl_add_u32 v76, v76, 1, v70
	ds_read_b64 v[80:81], v74
	ds_read_b64 v[82:83], v76
	v_xor_b32_e32 v74, 16, v93
	v_xor_b32_e32 v76, 16, v94
	v_pk_mul_f32 v[4:5], v[4:5], v[68:69] op_sel_hi:[1,0]
	v_pk_mul_f32 v[6:7], v[6:7], v[68:69] op_sel_hi:[1,0]
	v_lshl_add_u32 v74, v74, 1, v70
	v_lshl_add_u32 v70, v76, 1, v70
	s_waitcnt lgkmcnt(4)
	v_mfma_f32_16x16x32_bf16 v[4:7], v[86:89], v[60:63], v[4:7]
	v_ashrrev_i32_e32 v73, 31, v72
	ds_read_b64 v[86:87], v74
	ds_read_b64 v[88:89], v70
	v_add_u32_e32 v70, s0, v100
	v_lshl_add_u64 v[72:73], v[0:1], 0, v[72:73]
	v_pk_mul_f32 v[16:17], v[16:17], v[68:69] op_sel_hi:[1,0]
	v_pk_mul_f32 v[18:19], v[18:19], v[68:69] op_sel_hi:[1,0]
	v_xad_u32 v74, v90, 48, v70
	v_xor_b32_e32 v76, 24, v91
	v_lshlrev_b64 v[72:73], 12, v[72:73]
	s_waitcnt lgkmcnt(2)
	v_mfma_f32_16x16x32_bf16 v[16:19], v[80:83], v[60:63], v[16:19]
	v_lshl_add_u32 v76, v76, 1, v70
	ds_read_b64 v[80:81], v74
	ds_read_b64 v[82:83], v76
	v_xor_b32_e32 v74, 24, v93
	v_lshl_add_u32 v74, v74, 1, v70
	v_xor_b32_e32 v76, 24, v94
	v_lshl_add_u64 v[72:73], v[84:85], 0, v[72:73]
	v_mfma_f32_16x16x32_bf16 v[4:7], v[96:99], v[64:67], v[4:7]
	v_lshl_add_u32 v70, v76, 1, v70
	ds_read_b64 v[96:97], v74
	ds_read_b64 v[98:99], v70
	global_store_dword v[72:73], v69, off
	v_xad_u32 v72, v90, 64, v101
	v_xor_b32_e32 v73, 32, v91
	v_mul_f32_e32 v70, 0x3fb8aa3b, v79
	v_lshl_add_u32 v73, v73, 1, v101
	ds_read_b64 v[76:77], v72 offset:9216
	ds_read_b64 v[78:79], v73 offset:9216
	v_pk_mul_f32 v[12:13], v[12:13], v[68:69] op_sel_hi:[1,0]
	v_pk_mul_f32 v[14:15], v[14:15], v[68:69] op_sel_hi:[1,0]
	v_xor_b32_e32 v72, 32, v93
	v_xor_b32_e32 v73, 32, v94
	v_exp_f32_e32 v70, v70
	s_waitcnt lgkmcnt(4)
	v_mfma_f32_16x16x32_bf16 v[12:15], v[80:83], v[60:63], v[12:15]
	v_sub_u32_e32 v69, 12, v92
	v_lshl_add_u32 v72, v72, 1, v101
	v_lshl_add_u32 v73, v73, 1, v101
	s_movk_i32 s0, 0x50
	v_pk_mul_f32 v[24:25], v[24:25], v[68:69] op_sel_hi:[1,0]
	v_pk_mul_f32 v[26:27], v[26:27], v[68:69] op_sel_hi:[1,0]
	ds_read_b64 v[80:81], v72 offset:9216
	ds_read_b64 v[82:83], v73 offset:9216
	v_xad_u32 v72, v90, s0, v101
	v_xor_b32_e32 v73, 40, v91
	s_waitcnt lgkmcnt(2)
	v_mfma_f32_16x16x32_bf16 v[24:27], v[76:79], v[60:63], v[24:27]
	v_lshl_add_u32 v73, v73, 1, v101
	ds_read_b64 v[76:77], v72 offset:11520
	ds_read_b64 v[78:79], v73 offset:11520
	v_xor_b32_e32 v72, 40, v93
	v_lshl_add_u32 v72, v72, 1, v101
	v_xor_b32_e32 v73, 40, v94
	v_fmac_f32_e32 v75, v71, v70
	s_movk_i32 s0, 0x60
	v_xor_b32_e32 v70, 48, v91
	v_mfma_f32_16x16x32_bf16 v[16:19], v[86:89], v[64:67], v[16:19]
	v_lshl_add_u32 v73, v73, 1, v101
	ds_read_b64 v[86:87], v72 offset:11520
	ds_read_b64 v[88:89], v73 offset:11520
	v_pk_mul_f32 v[20:21], v[20:21], v[68:69] op_sel_hi:[1,0]
	v_mfma_f32_16x16x32_bf16 v[12:15], v[96:99], v[64:67], v[12:15]
	v_mul_f32_e64 v22, v22, v68
	v_mul_f32_e64 v23, v23, v68
	v_cndmask_b32_e64 v96, v69, v95, s[6:7]
	v_xad_u32 v69, v90, s0, v101
	v_lshl_add_u32 v72, v70, 1, v101
	ds_read_b64 v[70:71], v69 offset:13824
	ds_read_b64 v[72:73], v72 offset:13824
	v_pk_mul_f32 v[32:33], v[32:33], v[68:69] op_sel_hi:[1,0]
	v_pk_mul_f32 v[34:35], v[34:35], v[68:69] op_sel_hi:[1,0]
	v_xor_b32_e32 v69, 48, v93
	v_lshl_add_u32 v69, v69, 1, v101
	v_xor_b32_e32 v74, 48, v94
	s_waitcnt lgkmcnt(0)
	v_mfma_f32_16x16x32_bf16 v[32:35], v[70:73], v[60:63], v[32:35]
	s_movk_i32 s0, 0x70
	v_xor_b32_e32 v70, 56, v91
	v_lshl_add_u32 v74, v74, 1, v101
	v_mfma_f32_16x16x32_bf16 v[20:23], v[76:79], v[60:63], v[20:23]
	ds_read_b64 v[76:77], v69 offset:13824
	ds_read_b64 v[78:79], v74 offset:13824
	v_xad_u32 v69, v90, s0, v101
	v_lshl_add_u32 v72, v70, 1, v101
	ds_read_b64 v[70:71], v69 offset:16128
	ds_read_b64 v[72:73], v72 offset:16128
	v_xor_b32_e32 v69, 56, v93
	v_lshl_add_u32 v69, v69, 1, v101
	v_xor_b32_e32 v74, 56, v94
	v_mfma_f32_16x16x32_bf16 v[24:27], v[80:83], v[64:67], v[24:27]
	v_lshl_add_u32 v74, v74, 1, v101
	ds_read_b64 v[80:81], v69 offset:16128
	ds_read_b64 v[82:83], v74 offset:16128
	v_pk_mul_f32 v[28:29], v[28:29], v[68:69] op_sel_hi:[1,0]
	v_pk_mul_f32 v[30:31], v[30:31], v[68:69] op_sel_hi:[1,0]
	v_ashrrev_i32_e32 v97, 31, v96
	v_mfma_f32_16x16x32_bf16 v[20:23], v[86:89], v[64:67], v[20:23]
	v_lshl_add_u64 v[0:1], v[0:1], 0, v[96:97]
	v_lshlrev_b64 v[0:1], 12, v[0:1]
	v_lshl_add_u64 v[0:1], v[84:85], 0, v[0:1]
	s_waitcnt lgkmcnt(2)
	v_mfma_f32_16x16x32_bf16 v[28:31], v[70:73], v[60:63], v[28:31]
	global_store_dword v[0:1], v75, off
	v_mfma_f32_16x16x32_bf16 v[32:35], v[76:79], v[64:67], v[32:35]
	s_waitcnt lgkmcnt(0)
	v_mfma_f32_16x16x32_bf16 v[28:31], v[80:83], v[64:67], v[28:31]
	s_and_saveexec_b64 s[0:1], vcc
	s_cbranch_execz .LBB0_644
	v_and_b32_e32 v0, 7, v3
	v_ashrrev_i32_e32 v1, 3, v3
	v_cmp_eq_u32_e32 vcc, 0, v0
	s_and_saveexec_b64 s[12:13], vcc
	s_cbranch_execz .LBB0_643
	s_and_b64 s[66:67], s[14:15], exec
	s_cselect_b32 s66, s55, s64
	s_add_i32 s67, 16, 0x1c900
	s_add_i32 vcc_lo, 16, 0x25900
	s_and_b64 s[64:65], s[14:15], exec
	s_cselect_b32 s64, vcc_lo, s67
	v_lshlrev_b32_e32 v3, 2, v1
	v_add_u32_e32 v60, s64, v3
	v_add_u32_e32 v3, s66, v3
	s_waitcnt vmcnt(17)
	ds_write_b32 v3, v122
	ds_write_b32 v60, v110
	s_branch .LBB0_643
